# GDN prep gates section: the two vmcnt waits that only drained the previous direction's stores removed (gate columns were waited at tile staging)
# speedup vs baseline: 1.0077x; 1.0038x over previous
; DI void gdn_prep_item(const P& p, int l, int item, unsigned char* smem) {
;     ...
;     if (sub == 0) {
;         const float a_in = dir ? a_raw1 : a_raw0, b_in = dir ? b_raw1 : b_raw0;
;         const float A = __expf(p.gdn_alog[(l * 2 + dir) * 4 + h]);
;         const float xx = a_in + p.gdn_dtb[(l * 2 + dir) * 4 + h];
;         const float sp = fmaxf(xx, 0.f) + log1pf(__expf(-fabsf(xx)));
;         sg[i] = -A * sp; sbeta[i] = __builtin_amdgcn_rcpf(1.f + __expf(-b_in));
;     }
.LBB0_322:
	v_cndmask_b32_e64 v16, v103, v91, s[36:37]
	v_lshlrev_b32_e32 v18, 2, v16
	v_add_u32_e32 v17, s44, v18
	s_and_saveexec_b64 s[82:83], s[0:1]
	s_cbranch_execz .LBB0_324
	s_lshl_b32 s2, s31, 2
	s_or_b32 s2, s2, s30
	s_ashr_i32 s3, s2, 31
	s_mov_b32 s89, s19
	s_lshl_b64 s[2:3], s[2:3], 2
	v_readlane_b32 s12, v254, 47
	v_readlane_b32 s13, v254, 48
	s_add_u32 s12, s12, s2
	s_addc_u32 s13, s13, s3
	s_load_dword s4, s[12:13], 0x0
	v_readlane_b32 s14, v254, 49
	v_readlane_b32 s15, v254, 50
	s_add_u32 s2, s14, s2
	s_addc_u32 s3, s15, s3
	s_load_dword s5, s[2:3], 0x0
	v_cndmask_b32_e64 v20, v95, v93, s[36:37]
	v_cndmask_b32_e64 v19, v99, v97, s[36:37]
	v_mul_f32_e32 v19, 0xbfb8aa3b, v19
	v_exp_f32_e32 v19, v19
	v_readlane_b32 s16, v254, 51
	v_readlane_b32 s19, v254, 54
	s_mov_b32 s19, s89
	v_add_f32_e32 v19, 1.0, v19
	v_rcp_f32_e32 v19, v19
	s_mov_b32 s16, s29
	v_readlane_b32 s6, v254, 41
	v_readlane_b32 s7, v254, 42
	v_readlane_b32 s8, v254, 43
	v_readlane_b32 s9, v254, 44
	v_readlane_b32 s10, v254, 45
	v_readlane_b32 s11, v254, 46
	v_readlane_b32 s17, v254, 52
	v_readlane_b32 s18, v254, 53
	ds_write_b32 v17, v19
	s_waitcnt lgkmcnt(0)
	v_mov_b32_e32 v21, s4
	v_mul_f32_e32 v21, 0x3fb8aa3b, v21
	v_exp_f32_e32 v22, v21
	v_mov_b32_e32 v21, s5
	s_mov_b32 s2, 0xbfb8aa3b
	v_add_f32_e32 v20, v20, v21
	v_max_f32_e32 v23, 0, v20
	v_mul_f32_e64 v20, |v20|, s2
	v_exp_f32_e32 v24, v20
	s_mov_b32 s2, 0x3f2aaaab
	v_add_f32_e32 v25, 1.0, v24
	v_add_f32_e32 v20, -1.0, v25
	v_sub_f32_e32 v21, v20, v25
	v_add_f32_e32 v21, 1.0, v21
	v_sub_f32_e32 v20, v24, v20
	v_add_f32_e32 v26, v20, v21
	v_frexp_mant_f32_e32 v20, v25
	v_cmp_gt_f32_e32 vcc, s2, v20
	v_cvt_f64_f32_e32 v[20:21], v25
	v_frexp_exp_i32_f64_e32 v20, v[20:21]
	v_subbrev_co_u32_e32 v20, vcc, 0, v20, vcc
	v_sub_u32_e32 v21, 0, v20
	v_ldexp_f32 v25, v25, v21
	v_ldexp_f32 v21, v26, v21
	v_add_f32_e32 v26, -1.0, v25
	v_add_f32_e32 v27, 1.0, v26
	v_sub_f32_e32 v27, v25, v27
	v_add_f32_e32 v27, v21, v27
	v_add_f32_e32 v28, v26, v27
	v_sub_f32_e32 v26, v28, v26
	v_sub_f32_e32 v26, v27, v26
	v_add_f32_e32 v27, 1.0, v25
	v_add_f32_e32 v29, -1.0, v27
	v_sub_f32_e32 v25, v25, v29
	v_add_f32_e32 v21, v21, v25
	v_add_f32_e32 v25, v27, v21
	v_sub_f32_e32 v27, v25, v27
	v_sub_f32_e32 v21, v21, v27
	v_rcp_f32_e32 v27, v25
	v_cvt_f32_i32_e32 v20, v20
	s_mov_b32 s2, 0x3f317218
	v_mul_f32_e32 v29, v28, v27
	v_mul_f32_e32 v30, v25, v29
	v_fma_f32 v31, v29, v25, -v30
	v_fmac_f32_e32 v31, v29, v21
	v_add_f32_e32 v122, v30, v31
	v_sub_f32_e32 v123, v28, v122
	v_sub_f32_e32 v28, v28, v123
	v_sub_f32_e32 v30, v122, v30
	v_sub_f32_e32 v28, v28, v122
	v_add_f32_e32 v26, v26, v28
	v_sub_f32_e32 v28, v30, v31
	v_add_f32_e32 v26, v28, v26
	v_add_f32_e32 v28, v123, v26
	v_mul_f32_e32 v30, v27, v28
	v_mul_f32_e32 v31, v25, v30
	v_fma_f32 v25, v30, v25, -v31
	v_fmac_f32_e32 v25, v30, v21
	v_sub_f32_e32 v21, v123, v28
	v_add_f32_e32 v21, v26, v21
	v_add_f32_e32 v26, v31, v25
	v_sub_f32_e32 v122, v28, v26
	v_sub_f32_e32 v28, v28, v122
	v_sub_f32_e32 v31, v26, v31
	v_sub_f32_e32 v26, v28, v26
	v_add_f32_e32 v21, v21, v26
	v_sub_f32_e32 v25, v31, v25
	v_add_f32_e32 v21, v25, v21
	v_add_f32_e32 v25, v29, v30
	v_add_f32_e32 v21, v122, v21
	v_sub_f32_e32 v26, v25, v29
	v_mul_f32_e32 v21, v27, v21
	v_sub_f32_e32 v26, v30, v26
	v_add_f32_e32 v21, v26, v21
	v_mul_f32_e32 v29, 0x3f317218, v20
	v_add_f32_e32 v26, v25, v21
	v_fma_f32 v30, v20, s2, -v29
	v_mul_f32_e32 v27, v26, v26
	v_mov_b32_e32 v28, 0x3ecc95a3
	v_fmac_f32_e32 v30, 0xb102e308, v20
	v_sub_f32_e32 v20, v26, v25
	v_fmamk_f32 v28, v27, 0x3e9b6dac, v28
	v_sub_f32_e32 v20, v21, v20
	v_add_f32_e32 v21, v29, v30
	v_fmaak_f32 v28, v27, v28, 0x3f2aaada
	v_sub_f32_e32 v25, v21, v29
	v_ldexp_f32 v29, v26, 1
	v_mul_f32_e32 v26, v26, v27
	v_mul_f32_e32 v26, v26, v28
	v_add_f32_e32 v27, v29, v26
	v_sub_f32_e32 v28, v27, v29
	v_ldexp_f32 v20, v20, 1
	v_sub_f32_e32 v26, v26, v28
	v_add_f32_e32 v20, v20, v26
	v_add_f32_e32 v26, v27, v20
	v_sub_f32_e32 v27, v26, v27
	v_sub_f32_e32 v20, v20, v27
	v_add_f32_e32 v27, v21, v26
	v_sub_f32_e32 v28, v27, v21
	v_sub_f32_e32 v29, v27, v28
	v_sub_f32_e32 v25, v30, v25
	v_sub_f32_e32 v21, v21, v29
	v_sub_f32_e32 v26, v26, v28
	v_add_f32_e32 v21, v26, v21
	v_add_f32_e32 v26, v25, v20
	v_sub_f32_e32 v28, v26, v25
	v_sub_f32_e32 v29, v26, v28
	v_sub_f32_e32 v25, v25, v29
	v_sub_f32_e32 v20, v20, v28
	v_add_f32_e32 v21, v26, v21
	v_add_f32_e32 v20, v20, v25
	v_add_f32_e32 v25, v27, v21
	v_sub_f32_e32 v26, v25, v27
	v_sub_f32_e32 v21, v21, v26
	v_add_f32_e32 v20, v20, v21
	s_mov_b32 s2, 0x7f800000
	v_add_f32_e32 v20, v25, v20
	v_cmp_neq_f32_e32 vcc, s2, v24
	v_mov_b32_e32 v21, 0x7f800000
	s_mov_b32 s2, 0x33800000
	v_cndmask_b32_e32 v20, v21, v20, vcc
	v_cmp_ngt_f32_e32 vcc, -1.0, v24
	v_mov_b32_e32 v21, 0x7fc00000
	s_nop 0
	v_cndmask_b32_e32 v20, v21, v20, vcc
	v_cmp_neq_f32_e32 vcc, -1.0, v24
	v_mov_b32_e32 v21, 0xff800000
	s_nop 0
	v_cndmask_b32_e32 v20, v21, v20, vcc
	v_cmp_lt_f32_e64 vcc, |v24|, s2
	v_add_u32_e32 v21, s28, v18
	s_nop 0
	v_cndmask_b32_e32 v20, v20, v24, vcc
	v_add_f32_e32 v20, v23, v20
	v_mul_f32_e64 v20, v20, -v22
	ds_write_b32 v21, v20
